# barrier waiters poll the top-level generation; P0a: conversion loop keeps the prefetch in flight, adaLN GEMV loads batched, silu prologue loads batched
# speedup vs baseline: 1.1235x; 1.0330x over previous
.LBB0_383:
	v_readlane_b32 s0, v248, 46
	v_readlane_b32 s1, v248, 47
	s_waitcnt lgkmcnt(2)
	v_mov_b32_e32 v34, v0
	s_andn2_b64 vcc, exec, s[0:1]
	v_readlane_b32 s36, v248, 0
	s_cbranch_vccnz .LBB0_399
	v_mov_b32_e32 v22, v0
	v_lshlrev_b32_e32 v4, 2, v0
	s_add_u32 s0, s88, 0x1000
	s_addc_u32 s1, s89, 0
	global_load_dword v36, v4, s[90:91]
	global_load_dword v37, v4, s[90:91] offset:1024
	global_load_dword v38, v4, s[90:91] offset:2048
	global_load_dword v39, v4, s[90:91] offset:3072
	global_load_dword v40, v4, s[88:89]
	global_load_dword v41, v4, s[88:89] offset:1024
	global_load_dword v42, v4, s[88:89] offset:2048
	global_load_dword v43, v4, s[88:89] offset:3072
	global_load_dword v44, v4, s[0:1]
	global_load_dword v45, v4, s[0:1] offset:1024
	global_load_dword v46, v4, s[0:1] offset:2048
	global_load_dword v47, v4, s[0:1] offset:3072
	s_waitcnt vmcnt(11)
	v_mul_f32_e32 v3, 0xbfb8aa3b, v36
	v_exp_f32_e32 v3, v3
	s_nop 0
	v_add_f32_e32 v3, 1.0, v3
	v_div_scale_f32 v7, s[22:23], v3, v3, v36
	v_rcp_f32_e32 v8, v7
	s_nop 0
	v_fma_f32 v9, -v7, v8, 1.0
	v_fmac_f32_e32 v8, v9, v8
	v_div_scale_f32 v9, vcc, v36, v3, v36
	v_mul_f32_e32 v10, v9, v8
	v_fma_f32 v11, -v7, v10, v9
	v_fmac_f32_e32 v10, v11, v8
	v_fma_f32 v7, -v7, v10, v9
	v_div_fmas_f32 v7, v7, v8, v10
	v_div_fixup_f32 v2, v7, v3, v36
	ds_write_b32 v4, v2
	s_waitcnt vmcnt(10)
	v_mul_f32_e32 v3, 0xbfb8aa3b, v37
	v_exp_f32_e32 v3, v3
	s_nop 0
	v_add_f32_e32 v3, 1.0, v3
	v_div_scale_f32 v7, s[22:23], v3, v3, v37
	v_rcp_f32_e32 v8, v7
	s_nop 0
	v_fma_f32 v9, -v7, v8, 1.0
	v_fmac_f32_e32 v8, v9, v8
	v_div_scale_f32 v9, vcc, v37, v3, v37
	v_mul_f32_e32 v10, v9, v8
	v_fma_f32 v11, -v7, v10, v9
	v_fmac_f32_e32 v10, v11, v8
	v_fma_f32 v7, -v7, v10, v9
	v_div_fmas_f32 v7, v7, v8, v10
	v_div_fixup_f32 v2, v7, v3, v37
	ds_write_b32 v4, v2 offset:1024
	s_waitcnt vmcnt(9)
	v_mul_f32_e32 v3, 0xbfb8aa3b, v38
	v_exp_f32_e32 v3, v3
	s_nop 0
	v_add_f32_e32 v3, 1.0, v3
	v_div_scale_f32 v7, s[22:23], v3, v3, v38
	v_rcp_f32_e32 v8, v7
	s_nop 0
	v_fma_f32 v9, -v7, v8, 1.0
	v_fmac_f32_e32 v8, v9, v8
	v_div_scale_f32 v9, vcc, v38, v3, v38
	v_mul_f32_e32 v10, v9, v8
	v_fma_f32 v11, -v7, v10, v9
	v_fmac_f32_e32 v10, v11, v8
	v_fma_f32 v7, -v7, v10, v9
	v_div_fmas_f32 v7, v7, v8, v10
	v_div_fixup_f32 v2, v7, v3, v38
	ds_write_b32 v4, v2 offset:2048
	s_waitcnt vmcnt(8)
	v_mul_f32_e32 v3, 0xbfb8aa3b, v39
	v_exp_f32_e32 v3, v3
	s_nop 0
	v_add_f32_e32 v3, 1.0, v3
	v_div_scale_f32 v7, s[22:23], v3, v3, v39
	v_rcp_f32_e32 v8, v7
	s_nop 0
	v_fma_f32 v9, -v7, v8, 1.0
	v_fmac_f32_e32 v8, v9, v8
	v_div_scale_f32 v9, vcc, v39, v3, v39
	v_mul_f32_e32 v10, v9, v8
	v_fma_f32 v11, -v7, v10, v9
	v_fmac_f32_e32 v10, v11, v8
	v_fma_f32 v7, -v7, v10, v9
	v_div_fmas_f32 v7, v7, v8, v10
	v_div_fixup_f32 v2, v7, v3, v39
	ds_write_b32 v4, v2 offset:3072
	s_waitcnt vmcnt(7)
	v_mul_f32_e32 v3, 0xbfb8aa3b, v40
	v_exp_f32_e32 v3, v3
	s_nop 0
	v_add_f32_e32 v3, 1.0, v3
	v_div_scale_f32 v7, s[22:23], v3, v3, v40
	v_rcp_f32_e32 v8, v7
	s_nop 0
	v_fma_f32 v9, -v7, v8, 1.0
	v_fmac_f32_e32 v8, v9, v8
	v_div_scale_f32 v9, vcc, v40, v3, v40
	v_mul_f32_e32 v10, v9, v8
	v_fma_f32 v11, -v7, v10, v9
	v_fmac_f32_e32 v10, v11, v8
	v_fma_f32 v7, -v7, v10, v9
	v_div_fmas_f32 v7, v7, v8, v10
	v_div_fixup_f32 v2, v7, v3, v40
	ds_write_b32 v4, v2 offset:4096
	s_waitcnt vmcnt(6)
	v_mul_f32_e32 v3, 0xbfb8aa3b, v41
	v_exp_f32_e32 v3, v3
	s_nop 0
	v_add_f32_e32 v3, 1.0, v3
	v_div_scale_f32 v7, s[22:23], v3, v3, v41
	v_rcp_f32_e32 v8, v7
	s_nop 0
	v_fma_f32 v9, -v7, v8, 1.0
	v_fmac_f32_e32 v8, v9, v8
	v_div_scale_f32 v9, vcc, v41, v3, v41
	v_mul_f32_e32 v10, v9, v8
	v_fma_f32 v11, -v7, v10, v9
	v_fmac_f32_e32 v10, v11, v8
	v_fma_f32 v7, -v7, v10, v9
	v_div_fmas_f32 v7, v7, v8, v10
	v_div_fixup_f32 v2, v7, v3, v41
	ds_write_b32 v4, v2 offset:5120
	s_waitcnt vmcnt(5)
	v_mul_f32_e32 v3, 0xbfb8aa3b, v42
	v_exp_f32_e32 v3, v3
	s_nop 0
	v_add_f32_e32 v3, 1.0, v3
	v_div_scale_f32 v7, s[22:23], v3, v3, v42
	v_rcp_f32_e32 v8, v7
	s_nop 0
	v_fma_f32 v9, -v7, v8, 1.0
	v_fmac_f32_e32 v8, v9, v8
	v_div_scale_f32 v9, vcc, v42, v3, v42
	v_mul_f32_e32 v10, v9, v8
	v_fma_f32 v11, -v7, v10, v9
	v_fmac_f32_e32 v10, v11, v8
	v_fma_f32 v7, -v7, v10, v9
	v_div_fmas_f32 v7, v7, v8, v10
	v_div_fixup_f32 v2, v7, v3, v42
	ds_write_b32 v4, v2 offset:6144
	s_waitcnt vmcnt(4)
	v_mul_f32_e32 v3, 0xbfb8aa3b, v43
	v_exp_f32_e32 v3, v3
	s_nop 0
	v_add_f32_e32 v3, 1.0, v3
	v_div_scale_f32 v7, s[22:23], v3, v3, v43
	v_rcp_f32_e32 v8, v7
	s_nop 0
	v_fma_f32 v9, -v7, v8, 1.0
	v_fmac_f32_e32 v8, v9, v8
	v_div_scale_f32 v9, vcc, v43, v3, v43
	v_mul_f32_e32 v10, v9, v8
	v_fma_f32 v11, -v7, v10, v9
	v_fmac_f32_e32 v10, v11, v8
	v_fma_f32 v7, -v7, v10, v9
	v_div_fmas_f32 v7, v7, v8, v10
	v_div_fixup_f32 v2, v7, v3, v43
	ds_write_b32 v4, v2 offset:7168
	s_waitcnt vmcnt(3)
	v_mul_f32_e32 v3, 0xbfb8aa3b, v44
	v_exp_f32_e32 v3, v3
	s_nop 0
	v_add_f32_e32 v3, 1.0, v3
	v_div_scale_f32 v7, s[22:23], v3, v3, v44
	v_rcp_f32_e32 v8, v7
	s_nop 0
	v_fma_f32 v9, -v7, v8, 1.0
	v_fmac_f32_e32 v8, v9, v8
	v_div_scale_f32 v9, vcc, v44, v3, v44
	v_mul_f32_e32 v10, v9, v8
	v_fma_f32 v11, -v7, v10, v9
	v_fmac_f32_e32 v10, v11, v8
	v_fma_f32 v7, -v7, v10, v9
	v_div_fmas_f32 v7, v7, v8, v10
	v_div_fixup_f32 v2, v7, v3, v44
	ds_write_b32 v4, v2 offset:8192
	s_waitcnt vmcnt(2)
	v_mul_f32_e32 v3, 0xbfb8aa3b, v45
	v_exp_f32_e32 v3, v3
	s_nop 0
	v_add_f32_e32 v3, 1.0, v3
	v_div_scale_f32 v7, s[22:23], v3, v3, v45
	v_rcp_f32_e32 v8, v7
	s_nop 0
	v_fma_f32 v9, -v7, v8, 1.0
	v_fmac_f32_e32 v8, v9, v8
	v_div_scale_f32 v9, vcc, v45, v3, v45
	v_mul_f32_e32 v10, v9, v8
	v_fma_f32 v11, -v7, v10, v9
	v_fmac_f32_e32 v10, v11, v8
	v_fma_f32 v7, -v7, v10, v9
	v_div_fmas_f32 v7, v7, v8, v10
	v_div_fixup_f32 v2, v7, v3, v45
	ds_write_b32 v4, v2 offset:9216
	s_waitcnt vmcnt(1)
	v_mul_f32_e32 v3, 0xbfb8aa3b, v46
	v_exp_f32_e32 v3, v3
	s_nop 0
	v_add_f32_e32 v3, 1.0, v3
	v_div_scale_f32 v7, s[22:23], v3, v3, v46
	v_rcp_f32_e32 v8, v7
	s_nop 0
	v_fma_f32 v9, -v7, v8, 1.0
	v_fmac_f32_e32 v8, v9, v8
	v_div_scale_f32 v9, vcc, v46, v3, v46
	v_mul_f32_e32 v10, v9, v8
	v_fma_f32 v11, -v7, v10, v9
	v_fmac_f32_e32 v10, v11, v8
	v_fma_f32 v7, -v7, v10, v9
	v_div_fmas_f32 v7, v7, v8, v10
	v_div_fixup_f32 v2, v7, v3, v46
	ds_write_b32 v4, v2 offset:10240
	s_waitcnt vmcnt(0)
	v_mul_f32_e32 v3, 0xbfb8aa3b, v47
	v_exp_f32_e32 v3, v3
	s_nop 0
	v_add_f32_e32 v3, 1.0, v3
	v_div_scale_f32 v7, s[22:23], v3, v3, v47
	v_rcp_f32_e32 v8, v7
	s_nop 0
	v_fma_f32 v9, -v7, v8, 1.0
	v_fmac_f32_e32 v8, v9, v8
	v_div_scale_f32 v9, vcc, v47, v3, v47
	v_mul_f32_e32 v10, v9, v8
	v_fma_f32 v11, -v7, v10, v9
	v_fmac_f32_e32 v10, v11, v8
	v_fma_f32 v7, -v7, v10, v9
	v_div_fmas_f32 v7, v7, v8, v10
	v_div_fixup_f32 v2, v7, v3, v47
	ds_write_b32 v4, v2 offset:11264
	s_mov_b64 s[0:1], exec

.LBB0_395:
	global_load_dwordx4 v[44:47], v[18:19], off nt
	s_mov_b64 s[0:1], 0x3000
	v_lshl_add_u64 v[78:79], v[18:19], 0, s[0:1]
	global_load_dwordx4 v[48:51], v[78:79], off nt
	s_mov_b64 s[0:1], 0x6000
	v_lshl_add_u64 v[80:81], v[18:19], 0, s[0:1]
	global_load_dwordx4 v[52:55], v[80:81], off nt
	s_mov_b64 s[0:1], 0x9000
	v_lshl_add_u64 v[82:83], v[18:19], 0, s[0:1]
	global_load_dwordx4 v[56:59], v[82:83], off nt
	s_mov_b64 s[0:1], 0xc000
	v_lshl_add_u64 v[84:85], v[18:19], 0, s[0:1]
	global_load_dwordx4 v[60:63], v[84:85], off nt
	s_mov_b64 s[0:1], 0xf000
	v_lshl_add_u64 v[86:87], v[18:19], 0, s[0:1]
	global_load_dwordx4 v[64:67], v[86:87], off nt
	s_mov_b64 s[0:1], 0x12000
	v_lshl_add_u64 v[88:89], v[18:19], 0, s[0:1]
	global_load_dwordx4 v[68:71], v[88:89], off nt
	s_mov_b64 s[0:1], 0x15000
	v_lshl_add_u64 v[90:91], v[18:19], 0, s[0:1]
	global_load_dwordx4 v[72:75], v[90:91], off nt
	s_mov_b64 s[0:1], 0x18000
	v_lshl_add_u64 v[76:77], v[18:19], 0, s[0:1]
	global_load_dwordx4 v[100:103], v[76:77], off nt
	s_mov_b64 s[0:1], 0x1b000
	v_lshl_add_u64 v[78:79], v[18:19], 0, s[0:1]
	global_load_dwordx4 v[104:107], v[78:79], off nt
	s_mov_b64 s[0:1], 0x1e000
	v_lshl_add_u64 v[80:81], v[18:19], 0, s[0:1]
	global_load_dwordx4 v[108:111], v[80:81], off nt
	s_mov_b64 s[0:1], 0x21000
	v_lshl_add_u64 v[82:83], v[18:19], 0, s[0:1]
	global_load_dwordx4 v[112:115], v[82:83], off nt
	s_mov_b64 s[0:1], 0x24000
	v_lshl_add_u64 v[84:85], v[18:19], 0, s[0:1]
	global_load_dwordx4 v[116:119], v[84:85], off nt
	s_mov_b64 s[0:1], 0x27000
	v_lshl_add_u64 v[86:87], v[18:19], 0, s[0:1]
	global_load_dwordx4 v[120:123], v[86:87], off nt
	s_mov_b64 s[0:1], 0x2a000
	v_lshl_add_u64 v[88:89], v[18:19], 0, s[0:1]
	global_load_dwordx4 v[124:127], v[88:89], off nt
	s_mov_b64 s[0:1], 0x2d000
	v_lshl_add_u64 v[90:91], v[18:19], 0, s[0:1]
	global_load_dwordx4 v[128:131], v[90:91], off nt
	ds_read_b128 v[92:95], v23
	ds_read_b128 v[96:99], v23 offset:16
	ds_read_b128 v[132:135], v23 offset:4096
	ds_read_b128 v[136:139], v23 offset:4112
	ds_read_b128 v[36:39], v23 offset:8192
	ds_read_b128 v[40:43], v23 offset:8208
	v_add_u32_e32 v23, 32, v23
	s_waitcnt lgkmcnt(0)
	s_waitcnt vmcnt(15)
	v_pk_fma_f32 v[6:7], v[92:93], v[44:45], v[6:7] op_sel_hi:[0,1,1]
	v_pk_fma_f32 v[8:9], v[92:93], v[46:47], v[8:9] op_sel_hi:[0,1,1]
	v_pk_fma_f32 v[14:15], v[132:133], v[44:45], v[14:15] op_sel_hi:[0,1,1]
	v_pk_fma_f32 v[16:17], v[132:133], v[46:47], v[16:17] op_sel_hi:[0,1,1]
	v_pk_fma_f32 v[10:11], v[36:37], v[44:45], v[10:11] op_sel_hi:[0,1,1]
	v_pk_fma_f32 v[12:13], v[36:37], v[46:47], v[12:13] op_sel_hi:[0,1,1]
	s_waitcnt vmcnt(14)
	v_pk_fma_f32 v[6:7], v[92:93], v[48:49], v[6:7] op_sel:[1,0,0]
	v_pk_fma_f32 v[8:9], v[92:93], v[50:51], v[8:9] op_sel:[1,0,0]
	v_pk_fma_f32 v[14:15], v[132:133], v[48:49], v[14:15] op_sel:[1,0,0]
	v_pk_fma_f32 v[16:17], v[132:133], v[50:51], v[16:17] op_sel:[1,0,0]
	v_pk_fma_f32 v[10:11], v[36:37], v[48:49], v[10:11] op_sel:[1,0,0]
	v_pk_fma_f32 v[12:13], v[36:37], v[50:51], v[12:13] op_sel:[1,0,0]
	s_waitcnt vmcnt(13)
	v_pk_fma_f32 v[6:7], v[94:95], v[52:53], v[6:7] op_sel_hi:[0,1,1]
	v_pk_fma_f32 v[8:9], v[94:95], v[54:55], v[8:9] op_sel_hi:[0,1,1]
	v_pk_fma_f32 v[14:15], v[134:135], v[52:53], v[14:15] op_sel_hi:[0,1,1]
	v_pk_fma_f32 v[16:17], v[134:135], v[54:55], v[16:17] op_sel_hi:[0,1,1]
	v_pk_fma_f32 v[10:11], v[38:39], v[52:53], v[10:11] op_sel_hi:[0,1,1]
	v_pk_fma_f32 v[12:13], v[38:39], v[54:55], v[12:13] op_sel_hi:[0,1,1]
	s_waitcnt vmcnt(12)
	v_pk_fma_f32 v[6:7], v[94:95], v[56:57], v[6:7] op_sel:[1,0,0]
	v_pk_fma_f32 v[8:9], v[94:95], v[58:59], v[8:9] op_sel:[1,0,0]
	v_pk_fma_f32 v[14:15], v[134:135], v[56:57], v[14:15] op_sel:[1,0,0]
	v_pk_fma_f32 v[16:17], v[134:135], v[58:59], v[16:17] op_sel:[1,0,0]
	v_pk_fma_f32 v[10:11], v[38:39], v[56:57], v[10:11] op_sel:[1,0,0]
	v_pk_fma_f32 v[12:13], v[38:39], v[58:59], v[12:13] op_sel:[1,0,0]
	s_waitcnt vmcnt(11)
	v_pk_fma_f32 v[6:7], v[96:97], v[60:61], v[6:7] op_sel_hi:[0,1,1]
	v_pk_fma_f32 v[8:9], v[96:97], v[62:63], v[8:9] op_sel_hi:[0,1,1]
	v_pk_fma_f32 v[14:15], v[136:137], v[60:61], v[14:15] op_sel_hi:[0,1,1]
	v_pk_fma_f32 v[16:17], v[136:137], v[62:63], v[16:17] op_sel_hi:[0,1,1]
	v_pk_fma_f32 v[10:11], v[40:41], v[60:61], v[10:11] op_sel_hi:[0,1,1]
	v_pk_fma_f32 v[12:13], v[40:41], v[62:63], v[12:13] op_sel_hi:[0,1,1]
	s_waitcnt vmcnt(10)
	v_pk_fma_f32 v[6:7], v[96:97], v[64:65], v[6:7] op_sel:[1,0,0]
	v_pk_fma_f32 v[8:9], v[96:97], v[66:67], v[8:9] op_sel:[1,0,0]
	v_pk_fma_f32 v[14:15], v[136:137], v[64:65], v[14:15] op_sel:[1,0,0]
	v_pk_fma_f32 v[16:17], v[136:137], v[66:67], v[16:17] op_sel:[1,0,0]
	v_pk_fma_f32 v[10:11], v[40:41], v[64:65], v[10:11] op_sel:[1,0,0]
	v_pk_fma_f32 v[12:13], v[40:41], v[66:67], v[12:13] op_sel:[1,0,0]
	s_waitcnt vmcnt(9)
	v_pk_fma_f32 v[6:7], v[98:99], v[68:69], v[6:7] op_sel_hi:[0,1,1]
	v_pk_fma_f32 v[8:9], v[98:99], v[70:71], v[8:9] op_sel_hi:[0,1,1]
	v_pk_fma_f32 v[14:15], v[138:139], v[68:69], v[14:15] op_sel_hi:[0,1,1]
	v_pk_fma_f32 v[16:17], v[138:139], v[70:71], v[16:17] op_sel_hi:[0,1,1]
	v_pk_fma_f32 v[10:11], v[42:43], v[68:69], v[10:11] op_sel_hi:[0,1,1]
	v_pk_fma_f32 v[12:13], v[42:43], v[70:71], v[12:13] op_sel_hi:[0,1,1]
	s_waitcnt vmcnt(8)
	v_pk_fma_f32 v[6:7], v[98:99], v[72:73], v[6:7] op_sel:[1,0,0]
	v_pk_fma_f32 v[8:9], v[98:99], v[74:75], v[8:9] op_sel:[1,0,0]
	v_pk_fma_f32 v[14:15], v[138:139], v[72:73], v[14:15] op_sel:[1,0,0]
	v_pk_fma_f32 v[16:17], v[138:139], v[74:75], v[16:17] op_sel:[1,0,0]
	v_pk_fma_f32 v[10:11], v[42:43], v[72:73], v[10:11] op_sel:[1,0,0]
	v_pk_fma_f32 v[12:13], v[42:43], v[74:75], v[12:13] op_sel:[1,0,0]
	s_mov_b64 s[0:1], 0x30000
	v_lshl_add_u64 v[76:77], v[18:19], 0, s[0:1]
	global_load_dwordx4 v[44:47], v[76:77], off nt
	s_mov_b64 s[0:1], 0x33000
	v_lshl_add_u64 v[78:79], v[18:19], 0, s[0:1]
	global_load_dwordx4 v[48:51], v[78:79], off nt
	s_mov_b64 s[0:1], 0x36000
	v_lshl_add_u64 v[80:81], v[18:19], 0, s[0:1]
	global_load_dwordx4 v[52:55], v[80:81], off nt
	s_mov_b64 s[0:1], 0x39000
	v_lshl_add_u64 v[82:83], v[18:19], 0, s[0:1]
	global_load_dwordx4 v[56:59], v[82:83], off nt
	s_mov_b64 s[0:1], 0x3c000
	v_lshl_add_u64 v[84:85], v[18:19], 0, s[0:1]
	global_load_dwordx4 v[60:63], v[84:85], off nt
	s_mov_b64 s[0:1], 0x3f000
	v_lshl_add_u64 v[86:87], v[18:19], 0, s[0:1]
	global_load_dwordx4 v[64:67], v[86:87], off nt
	s_mov_b64 s[0:1], 0x42000
	v_lshl_add_u64 v[88:89], v[18:19], 0, s[0:1]
	global_load_dwordx4 v[68:71], v[88:89], off nt
	s_mov_b64 s[0:1], 0x45000
	v_lshl_add_u64 v[90:91], v[18:19], 0, s[0:1]
	global_load_dwordx4 v[72:75], v[90:91], off nt
	ds_read_b128 v[92:95], v23
	ds_read_b128 v[96:99], v23 offset:16
	ds_read_b128 v[132:135], v23 offset:4096
	ds_read_b128 v[136:139], v23 offset:4112
	ds_read_b128 v[36:39], v23 offset:8192
	ds_read_b128 v[40:43], v23 offset:8208
	v_add_u32_e32 v23, 32, v23
	s_waitcnt lgkmcnt(0)
	s_waitcnt vmcnt(15)
	v_pk_fma_f32 v[6:7], v[92:93], v[100:101], v[6:7] op_sel_hi:[0,1,1]
	v_pk_fma_f32 v[8:9], v[92:93], v[102:103], v[8:9] op_sel_hi:[0,1,1]
	v_pk_fma_f32 v[14:15], v[132:133], v[100:101], v[14:15] op_sel_hi:[0,1,1]
	v_pk_fma_f32 v[16:17], v[132:133], v[102:103], v[16:17] op_sel_hi:[0,1,1]
	v_pk_fma_f32 v[10:11], v[36:37], v[100:101], v[10:11] op_sel_hi:[0,1,1]
	v_pk_fma_f32 v[12:13], v[36:37], v[102:103], v[12:13] op_sel_hi:[0,1,1]
	s_waitcnt vmcnt(14)
	v_pk_fma_f32 v[6:7], v[92:93], v[104:105], v[6:7] op_sel:[1,0,0]
	v_pk_fma_f32 v[8:9], v[92:93], v[106:107], v[8:9] op_sel:[1,0,0]
	v_pk_fma_f32 v[14:15], v[132:133], v[104:105], v[14:15] op_sel:[1,0,0]
	v_pk_fma_f32 v[16:17], v[132:133], v[106:107], v[16:17] op_sel:[1,0,0]
	v_pk_fma_f32 v[10:11], v[36:37], v[104:105], v[10:11] op_sel:[1,0,0]
	v_pk_fma_f32 v[12:13], v[36:37], v[106:107], v[12:13] op_sel:[1,0,0]
	s_waitcnt vmcnt(13)
	v_pk_fma_f32 v[6:7], v[94:95], v[108:109], v[6:7] op_sel_hi:[0,1,1]
	v_pk_fma_f32 v[8:9], v[94:95], v[110:111], v[8:9] op_sel_hi:[0,1,1]
	v_pk_fma_f32 v[14:15], v[134:135], v[108:109], v[14:15] op_sel_hi:[0,1,1]
	v_pk_fma_f32 v[16:17], v[134:135], v[110:111], v[16:17] op_sel_hi:[0,1,1]
	v_pk_fma_f32 v[10:11], v[38:39], v[108:109], v[10:11] op_sel_hi:[0,1,1]
	v_pk_fma_f32 v[12:13], v[38:39], v[110:111], v[12:13] op_sel_hi:[0,1,1]
	s_waitcnt vmcnt(12)
	v_pk_fma_f32 v[6:7], v[94:95], v[112:113], v[6:7] op_sel:[1,0,0]
	v_pk_fma_f32 v[8:9], v[94:95], v[114:115], v[8:9] op_sel:[1,0,0]
	v_pk_fma_f32 v[14:15], v[134:135], v[112:113], v[14:15] op_sel:[1,0,0]
	v_pk_fma_f32 v[16:17], v[134:135], v[114:115], v[16:17] op_sel:[1,0,0]
	v_pk_fma_f32 v[10:11], v[38:39], v[112:113], v[10:11] op_sel:[1,0,0]
	v_pk_fma_f32 v[12:13], v[38:39], v[114:115], v[12:13] op_sel:[1,0,0]
	s_waitcnt vmcnt(11)
	v_pk_fma_f32 v[6:7], v[96:97], v[116:117], v[6:7] op_sel_hi:[0,1,1]
	v_pk_fma_f32 v[8:9], v[96:97], v[118:119], v[8:9] op_sel_hi:[0,1,1]
	v_pk_fma_f32 v[14:15], v[136:137], v[116:117], v[14:15] op_sel_hi:[0,1,1]
	v_pk_fma_f32 v[16:17], v[136:137], v[118:119], v[16:17] op_sel_hi:[0,1,1]
	v_pk_fma_f32 v[10:11], v[40:41], v[116:117], v[10:11] op_sel_hi:[0,1,1]
	v_pk_fma_f32 v[12:13], v[40:41], v[118:119], v[12:13] op_sel_hi:[0,1,1]
	s_waitcnt vmcnt(10)
	v_pk_fma_f32 v[6:7], v[96:97], v[120:121], v[6:7] op_sel:[1,0,0]
	v_pk_fma_f32 v[8:9], v[96:97], v[122:123], v[8:9] op_sel:[1,0,0]
	v_pk_fma_f32 v[14:15], v[136:137], v[120:121], v[14:15] op_sel:[1,0,0]
	v_pk_fma_f32 v[16:17], v[136:137], v[122:123], v[16:17] op_sel:[1,0,0]
	v_pk_fma_f32 v[10:11], v[40:41], v[120:121], v[10:11] op_sel:[1,0,0]
	v_pk_fma_f32 v[12:13], v[40:41], v[122:123], v[12:13] op_sel:[1,0,0]
	s_waitcnt vmcnt(9)
	v_pk_fma_f32 v[6:7], v[98:99], v[124:125], v[6:7] op_sel_hi:[0,1,1]
	v_pk_fma_f32 v[8:9], v[98:99], v[126:127], v[8:9] op_sel_hi:[0,1,1]
	v_pk_fma_f32 v[14:15], v[138:139], v[124:125], v[14:15] op_sel_hi:[0,1,1]
	v_pk_fma_f32 v[16:17], v[138:139], v[126:127], v[16:17] op_sel_hi:[0,1,1]
	v_pk_fma_f32 v[10:11], v[42:43], v[124:125], v[10:11] op_sel_hi:[0,1,1]
	v_pk_fma_f32 v[12:13], v[42:43], v[126:127], v[12:13] op_sel_hi:[0,1,1]
	s_waitcnt vmcnt(8)
	v_pk_fma_f32 v[6:7], v[98:99], v[128:129], v[6:7] op_sel:[1,0,0]
	v_pk_fma_f32 v[8:9], v[98:99], v[130:131], v[8:9] op_sel:[1,0,0]
	v_pk_fma_f32 v[14:15], v[138:139], v[128:129], v[14:15] op_sel:[1,0,0]
	v_pk_fma_f32 v[16:17], v[138:139], v[130:131], v[16:17] op_sel:[1,0,0]
	v_pk_fma_f32 v[10:11], v[42:43], v[128:129], v[10:11] op_sel:[1,0,0]
	v_pk_fma_f32 v[12:13], v[42:43], v[130:131], v[12:13] op_sel:[1,0,0]
	s_mov_b64 s[0:1], 0x48000
	v_lshl_add_u64 v[76:77], v[18:19], 0, s[0:1]
	global_load_dwordx4 v[100:103], v[76:77], off nt
	s_mov_b64 s[0:1], 0x4b000
	v_lshl_add_u64 v[78:79], v[18:19], 0, s[0:1]
	global_load_dwordx4 v[104:107], v[78:79], off nt
	s_mov_b64 s[0:1], 0x4e000
	v_lshl_add_u64 v[80:81], v[18:19], 0, s[0:1]
	global_load_dwordx4 v[108:111], v[80:81], off nt
	s_mov_b64 s[0:1], 0x51000
	v_lshl_add_u64 v[82:83], v[18:19], 0, s[0:1]
	global_load_dwordx4 v[112:115], v[82:83], off nt
	s_mov_b64 s[0:1], 0x54000
	v_lshl_add_u64 v[84:85], v[18:19], 0, s[0:1]
	global_load_dwordx4 v[116:119], v[84:85], off nt
	s_mov_b64 s[0:1], 0x57000
	v_lshl_add_u64 v[86:87], v[18:19], 0, s[0:1]
	global_load_dwordx4 v[120:123], v[86:87], off nt
	s_mov_b64 s[0:1], 0x5a000
	v_lshl_add_u64 v[88:89], v[18:19], 0, s[0:1]
	global_load_dwordx4 v[124:127], v[88:89], off nt
	s_mov_b64 s[0:1], 0x5d000
	v_lshl_add_u64 v[90:91], v[18:19], 0, s[0:1]
	global_load_dwordx4 v[128:131], v[90:91], off nt
	ds_read_b128 v[92:95], v23
	ds_read_b128 v[96:99], v23 offset:16
	ds_read_b128 v[132:135], v23 offset:4096
	ds_read_b128 v[136:139], v23 offset:4112
	ds_read_b128 v[36:39], v23 offset:8192
	ds_read_b128 v[40:43], v23 offset:8208
	v_add_u32_e32 v23, 32, v23
	s_waitcnt lgkmcnt(0)
	s_waitcnt vmcnt(15)
	v_pk_fma_f32 v[6:7], v[92:93], v[44:45], v[6:7] op_sel_hi:[0,1,1]
	v_pk_fma_f32 v[8:9], v[92:93], v[46:47], v[8:9] op_sel_hi:[0,1,1]
	v_pk_fma_f32 v[14:15], v[132:133], v[44:45], v[14:15] op_sel_hi:[0,1,1]
	v_pk_fma_f32 v[16:17], v[132:133], v[46:47], v[16:17] op_sel_hi:[0,1,1]
	v_pk_fma_f32 v[10:11], v[36:37], v[44:45], v[10:11] op_sel_hi:[0,1,1]
	v_pk_fma_f32 v[12:13], v[36:37], v[46:47], v[12:13] op_sel_hi:[0,1,1]
	s_waitcnt vmcnt(14)
	v_pk_fma_f32 v[6:7], v[92:93], v[48:49], v[6:7] op_sel:[1,0,0]
	v_pk_fma_f32 v[8:9], v[92:93], v[50:51], v[8:9] op_sel:[1,0,0]
	v_pk_fma_f32 v[14:15], v[132:133], v[48:49], v[14:15] op_sel:[1,0,0]
	v_pk_fma_f32 v[16:17], v[132:133], v[50:51], v[16:17] op_sel:[1,0,0]
	v_pk_fma_f32 v[10:11], v[36:37], v[48:49], v[10:11] op_sel:[1,0,0]
	v_pk_fma_f32 v[12:13], v[36:37], v[50:51], v[12:13] op_sel:[1,0,0]
	s_waitcnt vmcnt(13)
	v_pk_fma_f32 v[6:7], v[94:95], v[52:53], v[6:7] op_sel_hi:[0,1,1]
	v_pk_fma_f32 v[8:9], v[94:95], v[54:55], v[8:9] op_sel_hi:[0,1,1]
	v_pk_fma_f32 v[14:15], v[134:135], v[52:53], v[14:15] op_sel_hi:[0,1,1]
	v_pk_fma_f32 v[16:17], v[134:135], v[54:55], v[16:17] op_sel_hi:[0,1,1]
	v_pk_fma_f32 v[10:11], v[38:39], v[52:53], v[10:11] op_sel_hi:[0,1,1]
	v_pk_fma_f32 v[12:13], v[38:39], v[54:55], v[12:13] op_sel_hi:[0,1,1]
	s_waitcnt vmcnt(12)
	v_pk_fma_f32 v[6:7], v[94:95], v[56:57], v[6:7] op_sel:[1,0,0]
	v_pk_fma_f32 v[8:9], v[94:95], v[58:59], v[8:9] op_sel:[1,0,0]
	v_pk_fma_f32 v[14:15], v[134:135], v[56:57], v[14:15] op_sel:[1,0,0]
	v_pk_fma_f32 v[16:17], v[134:135], v[58:59], v[16:17] op_sel:[1,0,0]
	v_pk_fma_f32 v[10:11], v[38:39], v[56:57], v[10:11] op_sel:[1,0,0]
	v_pk_fma_f32 v[12:13], v[38:39], v[58:59], v[12:13] op_sel:[1,0,0]
	s_waitcnt vmcnt(11)
	v_pk_fma_f32 v[6:7], v[96:97], v[60:61], v[6:7] op_sel_hi:[0,1,1]
	v_pk_fma_f32 v[8:9], v[96:97], v[62:63], v[8:9] op_sel_hi:[0,1,1]
	v_pk_fma_f32 v[14:15], v[136:137], v[60:61], v[14:15] op_sel_hi:[0,1,1]
	v_pk_fma_f32 v[16:17], v[136:137], v[62:63], v[16:17] op_sel_hi:[0,1,1]
	v_pk_fma_f32 v[10:11], v[40:41], v[60:61], v[10:11] op_sel_hi:[0,1,1]
	v_pk_fma_f32 v[12:13], v[40:41], v[62:63], v[12:13] op_sel_hi:[0,1,1]
	s_waitcnt vmcnt(10)
	v_pk_fma_f32 v[6:7], v[96:97], v[64:65], v[6:7] op_sel:[1,0,0]
	v_pk_fma_f32 v[8:9], v[96:97], v[66:67], v[8:9] op_sel:[1,0,0]
	v_pk_fma_f32 v[14:15], v[136:137], v[64:65], v[14:15] op_sel:[1,0,0]
	v_pk_fma_f32 v[16:17], v[136:137], v[66:67], v[16:17] op_sel:[1,0,0]
	v_pk_fma_f32 v[10:11], v[40:41], v[64:65], v[10:11] op_sel:[1,0,0]
	v_pk_fma_f32 v[12:13], v[40:41], v[66:67], v[12:13] op_sel:[1,0,0]
	s_waitcnt vmcnt(9)
	v_pk_fma_f32 v[6:7], v[98:99], v[68:69], v[6:7] op_sel_hi:[0,1,1]
	v_pk_fma_f32 v[8:9], v[98:99], v[70:71], v[8:9] op_sel_hi:[0,1,1]
	v_pk_fma_f32 v[14:15], v[138:139], v[68:69], v[14:15] op_sel_hi:[0,1,1]
	v_pk_fma_f32 v[16:17], v[138:139], v[70:71], v[16:17] op_sel_hi:[0,1,1]
	v_pk_fma_f32 v[10:11], v[42:43], v[68:69], v[10:11] op_sel_hi:[0,1,1]
	v_pk_fma_f32 v[12:13], v[42:43], v[70:71], v[12:13] op_sel_hi:[0,1,1]
	s_waitcnt vmcnt(8)
	v_pk_fma_f32 v[6:7], v[98:99], v[72:73], v[6:7] op_sel:[1,0,0]
	v_pk_fma_f32 v[8:9], v[98:99], v[74:75], v[8:9] op_sel:[1,0,0]
	v_pk_fma_f32 v[14:15], v[138:139], v[72:73], v[14:15] op_sel:[1,0,0]
	v_pk_fma_f32 v[16:17], v[138:139], v[74:75], v[16:17] op_sel:[1,0,0]
	v_pk_fma_f32 v[10:11], v[42:43], v[72:73], v[10:11] op_sel:[1,0,0]
	v_pk_fma_f32 v[12:13], v[42:43], v[74:75], v[12:13] op_sel:[1,0,0]
	ds_read_b128 v[92:95], v23
	ds_read_b128 v[96:99], v23 offset:16
	ds_read_b128 v[132:135], v23 offset:4096
	ds_read_b128 v[136:139], v23 offset:4112
	ds_read_b128 v[36:39], v23 offset:8192
	ds_read_b128 v[40:43], v23 offset:8208
	v_add_u32_e32 v23, 32, v23
	s_waitcnt lgkmcnt(0)
	s_waitcnt vmcnt(7)
	v_pk_fma_f32 v[6:7], v[92:93], v[100:101], v[6:7] op_sel_hi:[0,1,1]
	v_pk_fma_f32 v[8:9], v[92:93], v[102:103], v[8:9] op_sel_hi:[0,1,1]
	v_pk_fma_f32 v[14:15], v[132:133], v[100:101], v[14:15] op_sel_hi:[0,1,1]
	v_pk_fma_f32 v[16:17], v[132:133], v[102:103], v[16:17] op_sel_hi:[0,1,1]
	v_pk_fma_f32 v[10:11], v[36:37], v[100:101], v[10:11] op_sel_hi:[0,1,1]
	v_pk_fma_f32 v[12:13], v[36:37], v[102:103], v[12:13] op_sel_hi:[0,1,1]
	s_waitcnt vmcnt(6)
	v_pk_fma_f32 v[6:7], v[92:93], v[104:105], v[6:7] op_sel:[1,0,0]
	v_pk_fma_f32 v[8:9], v[92:93], v[106:107], v[8:9] op_sel:[1,0,0]
	v_pk_fma_f32 v[14:15], v[132:133], v[104:105], v[14:15] op_sel:[1,0,0]
	v_pk_fma_f32 v[16:17], v[132:133], v[106:107], v[16:17] op_sel:[1,0,0]
	v_pk_fma_f32 v[10:11], v[36:37], v[104:105], v[10:11] op_sel:[1,0,0]
	v_pk_fma_f32 v[12:13], v[36:37], v[106:107], v[12:13] op_sel:[1,0,0]
	s_waitcnt vmcnt(5)
	v_pk_fma_f32 v[6:7], v[94:95], v[108:109], v[6:7] op_sel_hi:[0,1,1]
	v_pk_fma_f32 v[8:9], v[94:95], v[110:111], v[8:9] op_sel_hi:[0,1,1]
	v_pk_fma_f32 v[14:15], v[134:135], v[108:109], v[14:15] op_sel_hi:[0,1,1]
	v_pk_fma_f32 v[16:17], v[134:135], v[110:111], v[16:17] op_sel_hi:[0,1,1]
	v_pk_fma_f32 v[10:11], v[38:39], v[108:109], v[10:11] op_sel_hi:[0,1,1]
	v_pk_fma_f32 v[12:13], v[38:39], v[110:111], v[12:13] op_sel_hi:[0,1,1]
	s_waitcnt vmcnt(4)
	v_pk_fma_f32 v[6:7], v[94:95], v[112:113], v[6:7] op_sel:[1,0,0]
	v_pk_fma_f32 v[8:9], v[94:95], v[114:115], v[8:9] op_sel:[1,0,0]
	v_pk_fma_f32 v[14:15], v[134:135], v[112:113], v[14:15] op_sel:[1,0,0]
	v_pk_fma_f32 v[16:17], v[134:135], v[114:115], v[16:17] op_sel:[1,0,0]
	v_pk_fma_f32 v[10:11], v[38:39], v[112:113], v[10:11] op_sel:[1,0,0]
	v_pk_fma_f32 v[12:13], v[38:39], v[114:115], v[12:13] op_sel:[1,0,0]
	s_waitcnt vmcnt(3)
	v_pk_fma_f32 v[6:7], v[96:97], v[116:117], v[6:7] op_sel_hi:[0,1,1]
	v_pk_fma_f32 v[8:9], v[96:97], v[118:119], v[8:9] op_sel_hi:[0,1,1]
	v_pk_fma_f32 v[14:15], v[136:137], v[116:117], v[14:15] op_sel_hi:[0,1,1]
	v_pk_fma_f32 v[16:17], v[136:137], v[118:119], v[16:17] op_sel_hi:[0,1,1]
	v_pk_fma_f32 v[10:11], v[40:41], v[116:117], v[10:11] op_sel_hi:[0,1,1]
	v_pk_fma_f32 v[12:13], v[40:41], v[118:119], v[12:13] op_sel_hi:[0,1,1]
	s_waitcnt vmcnt(2)
	v_pk_fma_f32 v[6:7], v[96:97], v[120:121], v[6:7] op_sel:[1,0,0]
	v_pk_fma_f32 v[8:9], v[96:97], v[122:123], v[8:9] op_sel:[1,0,0]
	v_pk_fma_f32 v[14:15], v[136:137], v[120:121], v[14:15] op_sel:[1,0,0]
	v_pk_fma_f32 v[16:17], v[136:137], v[122:123], v[16:17] op_sel:[1,0,0]
	v_pk_fma_f32 v[10:11], v[40:41], v[120:121], v[10:11] op_sel:[1,0,0]
	v_pk_fma_f32 v[12:13], v[40:41], v[122:123], v[12:13] op_sel:[1,0,0]
	s_waitcnt vmcnt(1)
	v_pk_fma_f32 v[6:7], v[98:99], v[124:125], v[6:7] op_sel_hi:[0,1,1]
	v_pk_fma_f32 v[8:9], v[98:99], v[126:127], v[8:9] op_sel_hi:[0,1,1]
	v_pk_fma_f32 v[14:15], v[138:139], v[124:125], v[14:15] op_sel_hi:[0,1,1]
	v_pk_fma_f32 v[16:17], v[138:139], v[126:127], v[16:17] op_sel_hi:[0,1,1]
	v_pk_fma_f32 v[10:11], v[42:43], v[124:125], v[10:11] op_sel_hi:[0,1,1]
	v_pk_fma_f32 v[12:13], v[42:43], v[126:127], v[12:13] op_sel_hi:[0,1,1]
	s_waitcnt vmcnt(0)
	v_pk_fma_f32 v[6:7], v[98:99], v[128:129], v[6:7] op_sel:[1,0,0]
	v_pk_fma_f32 v[8:9], v[98:99], v[130:131], v[8:9] op_sel:[1,0,0]
	v_pk_fma_f32 v[14:15], v[138:139], v[128:129], v[14:15] op_sel:[1,0,0]
	v_pk_fma_f32 v[16:17], v[138:139], v[130:131], v[16:17] op_sel:[1,0,0]
	v_pk_fma_f32 v[10:11], v[42:43], v[128:129], v[10:11] op_sel:[1,0,0]
	v_pk_fma_f32 v[12:13], v[42:43], v[130:131], v[12:13] op_sel:[1,0,0]
	s_mov_b64 s[0:1], 0x60000
	s_movk_i32 s0, 0x60
	v_mul_lo_u32 v2, v22, 48
	v_cmp_gt_i32_e32 vcc, s0, v22
	ds_write_b128 v2, v[6:9] offset:12288
	ds_write_b128 v2, v[14:17] offset:12304
	ds_write_b128 v2, v[10:13] offset:12320
	s_waitcnt lgkmcnt(0)
	s_barrier
	s_and_saveexec_b64 s[0:1], vcc
	s_cbranch_execz .LBB0_398
	v_and_b32_e32 v3, 3, v22
	v_ashrrev_i32_e32 v4, 5, v22
	v_lshlrev_b32_e32 v3, 2, v3
	v_bfe_u32 v2, v22, 2, 3
	v_lshl_or_b32 v3, v4, 4, v3
	v_mad_u32_u24 v6, v2, 48, v3
	v_add_u32_e32 v2, 0x3000, v6
	ds_read2_b32 v[2:3], v2 offset1:96
	v_and_b32_e32 v5, 31, v22
	v_readlane_b32 s2, v247, 6
	v_readlane_b32 s36, v248, 50
	v_readlane_b32 s40, v248, 54
	s_waitcnt lgkmcnt(0)
	v_add_f32_e32 v2, 0, v2
	v_add_f32_e32 v7, v2, v3
	v_add_u32_e32 v2, 0x3200, v6
	ds_read2_b32 v[2:3], v2 offset0:64 offset1:160
	v_readlane_b32 s41, v248, 55
	v_readlane_b32 s20, v247, 4
	v_readlane_b32 s37, v248, 51
	v_readlane_b32 s38, v248, 52
	s_waitcnt lgkmcnt(0)
	v_add_f32_e32 v2, v7, v2
	v_add_f32_e32 v7, v2, v3
	v_add_u32_e32 v2, 0x3400, v6
	ds_read2_b32 v[2:3], v2 offset0:128 offset1:224
	v_readlane_b32 s39, v248, 53
	v_readlane_b32 s42, v248, 56
	v_readlane_b32 s43, v248, 57
	v_readlane_b32 s44, v248, 58
	s_waitcnt lgkmcnt(0)
	v_add_f32_e32 v2, v7, v2
	v_add_f32_e32 v7, v2, v3
	v_add_u32_e32 v2, 0x3800, v6
	ds_read2_b32 v[2:3], v2 offset0:64 offset1:160
	v_readlane_b32 s45, v248, 59
	v_readlane_b32 s46, v248, 60
	v_readlane_b32 s47, v248, 61
	v_readlane_b32 s48, v248, 62
	s_waitcnt lgkmcnt(0)
	v_add_f32_e32 v2, v7, v2
	v_add_f32_e32 v7, v2, v3
	v_add_u32_e32 v2, 0x3c00, v6
	ds_read2_b32 v[2:3], v2 offset1:96
	v_readlane_b32 s49, v248, 63
	v_readlane_b32 s50, v247, 0
	v_readlane_b32 s51, v247, 1
	v_readlane_b32 s21, v247, 5
	s_waitcnt lgkmcnt(0)
	v_add_f32_e32 v2, v7, v2
	v_add_f32_e32 v7, v2, v3
	v_add_u32_e32 v2, 0x3e00, v6
	ds_read2_b32 v[2:3], v2 offset0:64 offset1:160
	s_waitcnt lgkmcnt(0)
	v_add_f32_e32 v2, v7, v2
	v_add_f32_e32 v7, v2, v3
	v_add_u32_e32 v2, 0x4000, v6
	ds_read2_b32 v[2:3], v2 offset0:128 offset1:224
	s_waitcnt lgkmcnt(0)
	v_add_f32_e32 v2, v7, v2
	v_add_f32_e32 v7, v2, v3
	v_add_u32_e32 v2, 0x4400, v6
	ds_read2_b32 v[2:3], v2 offset0:64 offset1:160
	s_waitcnt lgkmcnt(0)
	v_add_f32_e32 v2, v7, v2
	v_add_f32_e32 v7, v2, v3
	v_add_u32_e32 v2, 0x4800, v6
	ds_read2_b32 v[2:3], v2 offset1:96
	s_waitcnt lgkmcnt(0)
	v_add_f32_e32 v2, v7, v2
	v_add_f32_e32 v7, v2, v3
	v_add_u32_e32 v2, 0x4a00, v6
	ds_read2_b32 v[2:3], v2 offset0:64 offset1:160
	s_waitcnt lgkmcnt(0)
	v_add_f32_e32 v2, v7, v2
	v_add_f32_e32 v7, v2, v3
	v_add_u32_e32 v2, 0x4c00, v6
	ds_read2_b32 v[2:3], v2 offset0:128 offset1:224
	s_waitcnt lgkmcnt(0)
	v_add_f32_e32 v2, v7, v2
	v_add_f32_e32 v7, v2, v3
	v_add_u32_e32 v2, 0x5000, v6
	ds_read2_b32 v[2:3], v2 offset0:64 offset1:160
	s_waitcnt lgkmcnt(0)
	v_add_f32_e32 v2, v7, v2
	v_add_f32_e32 v7, v2, v3
	v_add_u32_e32 v2, 0x5400, v6
	ds_read2_b32 v[2:3], v2 offset1:96
	s_waitcnt lgkmcnt(0)
	v_add_f32_e32 v2, v7, v2
	v_add_f32_e32 v7, v2, v3
	v_add_u32_e32 v2, 0x5600, v6
	ds_read2_b32 v[2:3], v2 offset0:64 offset1:160
	s_waitcnt lgkmcnt(0)
	v_add_f32_e32 v2, v7, v2
	v_add_f32_e32 v7, v2, v3
	v_add_u32_e32 v2, 0x5800, v6
	ds_read2_b32 v[2:3], v2 offset0:128 offset1:224
	s_waitcnt lgkmcnt(0)
	v_add_f32_e32 v2, v7, v2
	v_add_f32_e32 v7, v2, v3
	v_add_u32_e32 v2, 0x5c00, v6
	ds_read2_b32 v[2:3], v2 offset0:64 offset1:160
	s_waitcnt lgkmcnt(0)
	v_add_f32_e32 v2, v7, v2
	v_add_f32_e32 v6, v2, v3
	v_or_b32_e32 v2, s2, v5
	v_ashrrev_i32_e32 v3, 31, v2
	v_lshl_add_u64 v[2:3], v[2:3], 2, s[40:41]
	global_load_dword v2, v[2:3], off
	v_readlane_b32 s2, v247, 7
	s_waitcnt vmcnt(0)
	v_add_f32_e32 v6, v6, v2
	v_add_u32_e32 v2, s2, v4
	s_movk_i32 s2, 0xc00
	v_mul_lo_u32 v2, v2, s2
	v_add_u32_e32 v2, s20, v2
	v_or_b32_e32 v2, v2, v5
	v_ashrrev_i32_e32 v3, 31, v2
	v_lshl_add_u64 v[2:3], v[2:3], 2, s[4:5]
	global_store_dword v[2:3], v6, off

.LBB0_417:
	s_add_i32 s41, s41, s42
	s_add_i32 s43, s43, s44
	s_andn2_b64 vcc, exec, s[0:1]
	s_mov_b32 s2, s47
	s_waitcnt vmcnt(4)
	v_mov_b32_e32 v2, v58
	v_mov_b32_e32 v3, v59
	v_mov_b32_e32 v4, v60
	v_mov_b32_e32 v5, v61
	v_mov_b32_e32 v6, v62
	v_mov_b32_e32 v7, v63
	v_mov_b32_e32 v8, v64
	v_mov_b32_e32 v9, v65
	v_mov_b32_e32 v10, v50
	v_mov_b32_e32 v11, v51
	v_mov_b32_e32 v12, v52
	v_mov_b32_e32 v13, v53
	v_mov_b32_e32 v14, v54
	v_mov_b32_e32 v15, v55
	v_mov_b32_e32 v16, v56
	v_mov_b32_e32 v17, v57
	v_mov_b32_e32 v18, v42
	v_mov_b32_e32 v19, v43
	v_mov_b32_e32 v20, v44
	v_mov_b32_e32 v21, v45
	v_mov_b32_e32 v22, v46
	v_mov_b32_e32 v23, v47
	v_mov_b32_e32 v24, v48
	v_mov_b32_e32 v25, v49
	v_mov_b32_e32 v26, v34
	v_mov_b32_e32 v27, v35
	v_mov_b32_e32 v28, v36
	v_mov_b32_e32 v29, v37
	v_mov_b32_e32 v30, v38
	v_mov_b32_e32 v31, v39
	v_mov_b32_e32 v32, v40
	v_mov_b32_e32 v33, v41
	s_cbranch_vccz .LBB0_455

.LBB0_435:
	v_add_u32_e32 v34, s38, v72
	v_add_u32_e32 v42, s38, v70
	v_add_u32_e32 v50, s38, v73
	v_add_u32_e32 v58, s38, v75
	v_ashrrev_i32_e32 v35, 31, v34
	v_ashrrev_i32_e32 v43, 31, v42
	v_ashrrev_i32_e32 v51, 31, v50
	v_ashrrev_i32_e32 v59, 31, v58
	v_mul_lo_u32 v36, s22, v35
	v_mul_lo_u32 v37, s23, v34
	v_mad_u64_u32 v[34:35], s[36:37], s22, v34, 0
	v_mul_lo_u32 v44, s22, v43
	v_mul_lo_u32 v45, s23, v42
	v_mad_u64_u32 v[42:43], s[36:37], s22, v42, 0
	v_mul_lo_u32 v52, s22, v51
	v_mul_lo_u32 v53, s23, v50
	v_mad_u64_u32 v[50:51], s[36:37], s22, v50, 0
	v_mul_lo_u32 v60, s22, v59
	v_mul_lo_u32 v61, s23, v58
	v_mad_u64_u32 v[58:59], s[36:37], s22, v58, 0
	v_add3_u32 v35, v35, v36, v37
	v_add_u32_e32 v36, s38, v71
	v_add3_u32 v43, v43, v44, v45
	v_add_u32_e32 v44, s38, v67
	v_add3_u32 v51, v51, v52, v53
	v_add_u32_e32 v52, s38, v74
	v_add3_u32 v59, v59, v60, v61
	v_add_u32_e32 v60, s38, v76
	v_ashrrev_i32_e32 v37, 31, v36
	v_ashrrev_i32_e32 v45, 31, v44
	v_ashrrev_i32_e32 v53, 31, v52
	v_ashrrev_i32_e32 v61, 31, v60
	v_mul_lo_u32 v38, s22, v37
	v_mul_lo_u32 v39, s23, v36
	v_mad_u64_u32 v[36:37], s[36:37], s22, v36, 0
	v_mul_lo_u32 v46, s22, v45
	v_mul_lo_u32 v47, s23, v44
	v_mad_u64_u32 v[44:45], s[36:37], s22, v44, 0
	v_mul_lo_u32 v54, s22, v53
	v_mul_lo_u32 v55, s23, v52
	v_mad_u64_u32 v[52:53], s[36:37], s22, v52, 0
	v_mul_lo_u32 v62, s22, v61
	v_mul_lo_u32 v63, s23, v60
	v_mad_u64_u32 v[60:61], s[22:23], s22, v60, 0
	s_ashr_i32 s25, s24, 31
	v_add3_u32 v37, v37, v38, v39
	v_add3_u32 v45, v45, v46, v47
	v_add3_u32 v53, v53, v54, v55
	v_add3_u32 v61, v61, v62, v63
	v_lshl_add_u64 v[34:35], v[34:35], 2, s[20:21]
	s_lshl_b64 s[24:25], s[24:25], 2
	v_lshl_add_u64 v[36:37], v[36:37], 2, s[20:21]
	v_lshl_add_u64 v[42:43], v[42:43], 2, s[20:21]
	v_lshl_add_u64 v[44:45], v[44:45], 2, s[20:21]
	v_lshl_add_u64 v[50:51], v[50:51], 2, s[20:21]
	v_lshl_add_u64 v[52:53], v[52:53], 2, s[20:21]
	v_lshl_add_u64 v[58:59], v[58:59], 2, s[20:21]
	v_lshl_add_u64 v[60:61], v[60:61], 2, s[20:21]
	v_lshl_add_u64 v[34:35], v[34:35], 0, s[24:25]
	v_lshlrev_b32_e32 v146, 2, v66
	v_lshl_add_u64 v[36:37], v[36:37], 0, s[24:25]
	v_lshl_add_u64 v[42:43], v[42:43], 0, s[24:25]
	v_lshl_add_u64 v[44:45], v[44:45], 0, s[24:25]
	v_lshl_add_u64 v[50:51], v[50:51], 0, s[24:25]
	v_lshl_add_u64 v[52:53], v[52:53], 0, s[24:25]
	v_lshl_add_u64 v[58:59], v[58:59], 0, s[24:25]
	v_lshl_add_u64 v[60:61], v[60:61], 0, s[24:25]
	v_lshl_add_u64 v[34:35], v[34:35], 0, v[146:147]
	v_lshl_add_u64 v[36:37], v[36:37], 0, v[146:147]
	v_lshl_add_u64 v[42:43], v[42:43], 0, v[146:147]
	v_lshl_add_u64 v[44:45], v[44:45], 0, v[146:147]
	v_lshl_add_u64 v[50:51], v[50:51], 0, v[146:147]
	v_lshl_add_u64 v[52:53], v[52:53], 0, v[146:147]
	v_lshl_add_u64 v[58:59], v[58:59], 0, v[146:147]
	v_lshl_add_u64 v[60:61], v[60:61], 0, v[146:147]
	global_load_dwordx4 v[38:41], v[34:35], off nt
	s_nop 0
	global_load_dwordx4 v[34:37], v[36:37], off nt
	s_nop 0
	global_load_dwordx4 v[46:49], v[42:43], off nt
	s_nop 0
	global_load_dwordx4 v[42:45], v[44:45], off nt
	s_nop 0
	global_load_dwordx4 v[54:57], v[50:51], off nt
	s_nop 0
	global_load_dwordx4 v[50:53], v[52:53], off nt
	s_nop 0
	global_load_dwordx4 v[62:65], v[58:59], off nt
	s_nop 0
	global_load_dwordx4 v[58:61], v[60:61], off nt
	s_branch .LBB0_436
.Lconv_nonext:
	s_waitcnt vmcnt(0)

.LBB0_450:
	v_add_u32_e32 v69, s22, v72
	v_mov_b64_e32 v[84:85], s[20:21]
	v_mad_i64_i32 v[86:87], s[36:37], v69, s93, v[84:85]
	s_ashr_i32 s25, s24, 31
	s_lshl_b64 s[36:37], s[24:25], 1
	v_lshl_add_u64 v[86:87], v[86:87], 0, s[36:37]
	v_lshlrev_b32_e32 v146, 1, v66
	v_lshl_add_u64 v[86:87], v[86:87], 0, v[146:147]
	s_waitcnt vmcnt(8)
	v_cvt_pk_bf16_f32 v89, v32, v33
	v_cvt_pk_bf16_f32 v88, v30, v31
	v_add_u32_e32 v69, s22, v71
	global_store_dwordx2 v[86:87], v[88:89], off
	v_mad_i64_i32 v[86:87], s[38:39], v69, s93, v[84:85]
	v_lshl_add_u64 v[86:87], v[86:87], 0, s[36:37]
	v_lshl_add_u64 v[86:87], v[86:87], 0, v[146:147]
	v_cvt_pk_bf16_f32 v89, v28, v29
	v_cvt_pk_bf16_f32 v88, v26, v27
	v_add_u32_e32 v69, s22, v70
	global_store_dwordx2 v[86:87], v[88:89], off
	v_mad_i64_i32 v[86:87], s[38:39], v69, s93, v[84:85]
	v_lshl_add_u64 v[86:87], v[86:87], 0, s[36:37]
	v_lshl_add_u64 v[86:87], v[86:87], 0, v[146:147]
	v_cvt_pk_bf16_f32 v89, v24, v25
	v_cvt_pk_bf16_f32 v88, v22, v23
	v_add_u32_e32 v69, s22, v67
	global_store_dwordx2 v[86:87], v[88:89], off
	v_mad_i64_i32 v[86:87], s[38:39], v69, s93, v[84:85]
	v_lshl_add_u64 v[86:87], v[86:87], 0, s[36:37]
	v_lshl_add_u64 v[86:87], v[86:87], 0, v[146:147]
	v_cvt_pk_bf16_f32 v89, v20, v21
	v_cvt_pk_bf16_f32 v88, v18, v19
	v_add_u32_e32 v69, s22, v73
	global_store_dwordx2 v[86:87], v[88:89], off
	v_mad_i64_i32 v[86:87], s[38:39], v69, s93, v[84:85]
	v_lshl_add_u64 v[86:87], v[86:87], 0, s[36:37]
	v_lshl_add_u64 v[86:87], v[86:87], 0, v[146:147]
	v_cvt_pk_bf16_f32 v89, v16, v17
	v_cvt_pk_bf16_f32 v88, v14, v15
	v_add_u32_e32 v69, s22, v74
	global_store_dwordx2 v[86:87], v[88:89], off
	v_mad_i64_i32 v[86:87], s[38:39], v69, s93, v[84:85]
	v_lshl_add_u64 v[86:87], v[86:87], 0, s[36:37]
	v_lshl_add_u64 v[86:87], v[86:87], 0, v[146:147]
	v_cvt_pk_bf16_f32 v89, v12, v13
	v_cvt_pk_bf16_f32 v88, v10, v11
	v_add_u32_e32 v69, s22, v75
	global_store_dwordx2 v[86:87], v[88:89], off
	v_mad_i64_i32 v[86:87], s[38:39], v69, s93, v[84:85]
	v_add_u32_e32 v69, s22, v76
	v_lshl_add_u64 v[86:87], v[86:87], 0, s[36:37]
	v_mad_i64_i32 v[84:85], s[38:39], v69, s93, v[84:85]
	v_lshl_add_u64 v[86:87], v[86:87], 0, v[146:147]
	v_cvt_pk_bf16_f32 v89, v8, v9
	v_cvt_pk_bf16_f32 v88, v6, v7
	v_lshl_add_u64 v[84:85], v[84:85], 0, s[36:37]
	global_store_dwordx2 v[86:87], v[88:89], off
	v_lshl_add_u64 v[84:85], v[84:85], 0, v[146:147]
	v_cvt_pk_bf16_f32 v87, v4, v5
	v_cvt_pk_bf16_f32 v86, v2, v3
	global_store_dwordx2 v[84:85], v[86:87], off
	s_cbranch_execnz .LBB0_417
	s_branch .LBB0_454

.LBB0_454:
	v_add_u32_e32 v83, 0x400, v82
	s_waitcnt vmcnt(8)
	ds_write2_b32 v78, v30, v31 offset1:1
	ds_write2_b32 v78, v32, v33 offset0:2 offset1:3
	ds_write2_b32 v79, v26, v27 offset1:1
	ds_write2_b32 v79, v28, v29 offset0:2 offset1:3
	ds_write2_b32 v80, v22, v23 offset1:1
	ds_write2_b32 v80, v24, v25 offset0:2 offset1:3
	ds_write2_b32 v81, v18, v19 offset1:1
	ds_write2_b32 v81, v20, v21 offset0:2 offset1:3
	s_waitcnt lgkmcnt(0)
	s_barrier
	ds_read2_b32 v[22:23], v82 offset1:65
	ds_read2_b32 v[18:19], v82 offset0:130 offset1:195
	ds_read2_b32 v[24:25], v83 offset0:4 offset1:69
	ds_read2_b32 v[20:21], v83 offset0:134 offset1:199
	v_add_u32_e32 v86, 0x800, v82
	v_add_u32_e32 v87, 0xc00, v82
	ds_read2_b32 v[26:27], v86 offset0:8 offset1:73
	ds_read2_b32 v[28:29], v86 offset0:138 offset1:203
	ds_read2_b32 v[30:31], v87 offset0:12 offset1:77
	ds_read2_b32 v[32:33], v87 offset0:142 offset1:207
	v_add_u32_e32 v69, s24, v77
	v_mov_b64_e32 v[84:85], s[20:21]
	v_mad_i64_i32 v[84:85], s[20:21], v69, s93, v[84:85]
	s_ashr_i32 s23, s22, 31
	v_lshl_add_u64 v[84:85], s[22:23], 1, v[84:85]
	v_mov_b32_e32 v69, v147
	v_lshl_add_u64 v[84:85], v[84:85], 0, v[68:69]
	s_waitcnt lgkmcnt(4)
	v_cvt_pk_bf16_f32 v21, v20, v21
	v_cvt_pk_bf16_f32 v20, v24, v25
	v_cvt_pk_bf16_f32 v19, v18, v19
	v_cvt_pk_bf16_f32 v18, v22, v23
	global_store_dwordx4 v[84:85], v[18:21], off
	s_waitcnt lgkmcnt(0)
	s_nop 0
	v_cvt_pk_bf16_f32 v21, v32, v33
	v_cvt_pk_bf16_f32 v20, v30, v31
	v_cvt_pk_bf16_f32 v19, v28, v29
	v_cvt_pk_bf16_f32 v18, v26, v27
	global_store_dwordx4 v[84:85], v[18:21], off offset:16
	s_barrier
	ds_write2_b32 v78, v14, v15 offset1:1
	ds_write2_b32 v78, v16, v17 offset0:2 offset1:3
	ds_write2_b32 v79, v10, v11 offset1:1
	ds_write2_b32 v79, v12, v13 offset0:2 offset1:3
	ds_write2_b32 v80, v6, v7 offset1:1
	ds_write2_b32 v80, v8, v9 offset0:2 offset1:3
	ds_write2_b32 v81, v2, v3 offset1:1
	ds_write2_b32 v81, v4, v5 offset0:2 offset1:3
	s_waitcnt lgkmcnt(0)
	s_barrier
	ds_read2_b32 v[6:7], v82 offset1:65
	ds_read2_b32 v[2:3], v82 offset0:130 offset1:195
	ds_read2_b32 v[8:9], v83 offset0:4 offset1:69
	ds_read2_b32 v[4:5], v83 offset0:134 offset1:199
	ds_read2_b32 v[10:11], v86 offset0:8 offset1:73
	ds_read2_b32 v[12:13], v86 offset0:138 offset1:203
	ds_read2_b32 v[14:15], v87 offset0:12 offset1:77
	ds_read2_b32 v[16:17], v87 offset0:142 offset1:207
	s_waitcnt lgkmcnt(4)
	v_cvt_pk_bf16_f32 v5, v4, v5
	v_cvt_pk_bf16_f32 v4, v8, v9
	v_cvt_pk_bf16_f32 v3, v2, v3
	v_cvt_pk_bf16_f32 v2, v6, v7
	global_store_dwordx4 v[84:85], v[2:5], off offset:128
	s_waitcnt lgkmcnt(0)
	s_nop 0
	v_cvt_pk_bf16_f32 v5, v16, v17
	v_cvt_pk_bf16_f32 v4, v14, v15
	v_cvt_pk_bf16_f32 v3, v12, v13
	v_cvt_pk_bf16_f32 v2, v10, v11
	global_store_dwordx4 v[84:85], v[2:5], off offset:144
	s_barrier
	s_branch .LBB0_417

.LBB0_509:
	s_or_b64 exec, exec, s[20:21]
	v_cvt_f32_u32_e32 v6, v4
	s_waitcnt vmcnt(0)
	v_readfirstlane_b32 s2, v5
	v_sub_u32_e32 v5, 0, v4
	v_rcp_iflag_f32_e32 v6, v6
	v_add_u32_e32 v7, s2, v3
	v_mul_f32_e32 v6, 0x4f7ffffe, v6
	v_cvt_u32_f32_e32 v6, v6
	v_mul_lo_u32 v3, v5, v6
	v_mul_hi_u32 v3, v6, v3
	v_add_u32_e32 v3, v6, v3
	v_mul_hi_u32 v3, v7, v3
	v_mul_lo_u32 v5, v3, v4
	v_sub_u32_e32 v5, v7, v5
	v_add_u32_e32 v6, 1, v3
	v_cmp_ge_u32_e32 vcc, v5, v4
	s_nop 1
	v_cndmask_b32_e32 v3, v3, v6, vcc
	v_sub_u32_e32 v6, v5, v4
	v_cndmask_b32_e32 v5, v5, v6, vcc
	v_add_u32_e32 v6, 1, v3
	v_cmp_ge_u32_e32 vcc, v5, v4
	v_add_u32_e32 v5, 1, v7
	s_nop 0
	v_cndmask_b32_e32 v3, v3, v6, vcc
	v_mul_lo_u32 v6, v4, v3
	v_add_u32_e32 v4, v6, v4
	v_cmp_ne_u32_e32 vcc, v5, v4
	s_and_saveexec_b64 s[20:21], vcc
	s_xor_b64 s[20:21], exec, s[20:21]
	s_cbranch_execz .LBB0_523
	v_readlane_b32 s22, v247, 63
	v_readlane_b32 s23, v246, 0
	s_waitcnt lgkmcnt(0)
	s_nop 3
	global_load_dword v2, v147, s[22:23] sc1
	s_waitcnt vmcnt(0)
	v_cmp_eq_u32_e32 vcc, v2, v3
	s_and_saveexec_b64 s[22:23], vcc
	s_cbranch_execz .LBB0_522
	s_mov_b32 s2, 1
	s_mov_b64 s[24:25], 0
	s_branch .LBB0_513

.LBB0_515:
	v_readlane_b32 s34, v247, 63
	v_readlane_b32 s35, v246, 0
	s_add_i32 s2, s2, 1
	s_mov_b64 s[40:41], -1
	s_nop 2
	global_load_dword v2, v147, s[34:35] sc1
	s_waitcnt vmcnt(0)
	v_cmp_ne_u32_e32 vcc, v2, v3
	s_orn2_b64 s[38:39], vcc, exec
	s_branch .LBB0_512
